# router weight staging issues its 16 loads together; cache conversion loops find their inputs prefetched
# speedup vs baseline: 1.0556x; 1.0046x over previous
.LBB0_89:
	s_or_b64 exec, exec, s[0:1]
	v_mov_b32_e32 v10, v187
	v_readlane_b32 s0, v247, 0
	s_barrier
	s_mov_b32 s1, 0x20000
	v_lshl_add_u32 v0, s0, 8, v10
	s_lshl_b32 s0, s84, 8
	v_cmp_gt_i32_e32 vcc, s1, v0
	v_ashrrev_i32_e32 v1, 31, v0
	s_and_saveexec_b64 s[2:3], vcc
	s_cbranch_execz .LBB0_94
	v_lshlrev_b64 v[2:3], 4, v[0:1]
	v_readlane_b32 s52, v247, 5
	v_readlane_b32 s53, v247, 6
	v_readlane_b32 s54, v247, 7
	v_readlane_b32 s55, v247, 8
	v_readlane_b32 s56, v247, 9
	v_readlane_b32 s57, v247, 10
	v_readlane_b32 s58, v247, 11
	v_readlane_b32 s59, v247, 12
	v_lshlrev_b32_e32 v100, 4, v0
	s_lshl_b32 s60, s84, 12
	v_add_u32_e32 v101, s60, v100
	s_nop 4
	global_load_dwordx4 v[104:107], v100, s[52:53]
	global_load_dwordx4 v[108:111], v100, s[54:55]
	global_load_dwordx4 v[112:115], v100, s[56:57]
	global_load_dwordx4 v[116:119], v101, s[56:57]
	global_load_dwordx4 v[120:123], v100, s[58:59]
	global_load_dwordx4 v[124:127], v101, s[58:59]
	v_readlane_b32 s36, v247, 1
	v_or_b32_e32 v2, 8, v2
	v_readlane_b32 s40, v247, 5
	v_readlane_b32 s41, v247, 6
	s_ashr_i32 s1, s0, 31
	v_lshlrev_b64 v[4:5], 3, v[0:1]
	v_lshl_add_u64 v[6:7], s[40:41], 0, v[2:3]
	s_lshl_b64 s[6:7], s[0:1], 4
	v_lshl_add_u64 v[8:9], s[26:27], 0, v[4:5]
	s_lshl_b64 s[8:9], s[0:1], 3
	s_mov_b64 s[10:11], 0
	s_mov_b32 s1, 0x1ffff
	v_mov_b32_e32 v11, v0
	v_readlane_b32 s37, v247, 2
	v_readlane_b32 s38, v247, 3
	v_readlane_b32 s39, v247, 4
	v_readlane_b32 s42, v247, 7
	v_readlane_b32 s43, v247, 8
	v_readlane_b32 s44, v247, 9
	v_readlane_b32 s45, v247, 10
	v_readlane_b32 s46, v247, 11
	v_readlane_b32 s47, v247, 12
	v_readlane_b32 s48, v247, 13
	v_readlane_b32 s49, v247, 14
	v_readlane_b32 s50, v247, 15
	v_readlane_b32 s51, v247, 16

.LBB0_1164:
	v_lshlrev_b32_e32 v9, 4, v8
	v_and_b32_e32 v3, 3, v8
	v_lshlrev_b32_e32 v3, 14, v3
	v_and_b32_e32 v5, -4, v8
	v_add3_u32 v3, 0, v3, v5
	global_load_dwordx4 v[100:103], v9, s[6:7]
	s_add_u32 s6, s6, 0x1000
	s_addc_u32 s7, s7, 0
	global_load_dwordx4 v[104:107], v9, s[6:7]
	s_add_u32 s6, s6, 0x1000
	s_addc_u32 s7, s7, 0
	global_load_dwordx4 v[108:111], v9, s[6:7]
	s_add_u32 s6, s6, 0x1000
	s_addc_u32 s7, s7, 0
	global_load_dwordx4 v[112:115], v9, s[6:7]
	s_add_u32 s6, s6, 0x1000
	s_addc_u32 s7, s7, 0
	global_load_dwordx4 v[116:119], v9, s[6:7]
	s_add_u32 s6, s6, 0x1000
	s_addc_u32 s7, s7, 0
	global_load_dwordx4 v[120:123], v9, s[6:7]
	s_add_u32 s6, s6, 0x1000
	s_addc_u32 s7, s7, 0
	global_load_dwordx4 v[124:127], v9, s[6:7]
	s_add_u32 s6, s6, 0x1000
	s_addc_u32 s7, s7, 0
	global_load_dwordx4 v[128:131], v9, s[6:7]
	s_add_u32 s6, s6, 0x1000
	s_addc_u32 s7, s7, 0
	global_load_dwordx4 v[132:135], v9, s[6:7]
	s_add_u32 s6, s6, 0x1000
	s_addc_u32 s7, s7, 0
	global_load_dwordx4 v[136:139], v9, s[6:7]
	s_add_u32 s6, s6, 0x1000
	s_addc_u32 s7, s7, 0
	global_load_dwordx4 v[140:143], v9, s[6:7]
	s_add_u32 s6, s6, 0x1000
	s_addc_u32 s7, s7, 0
	global_load_dwordx4 v[144:147], v9, s[6:7]
	s_add_u32 s6, s6, 0x1000
	s_addc_u32 s7, s7, 0
	global_load_dwordx4 v[148:151], v9, s[6:7]
	s_add_u32 s6, s6, 0x1000
	s_addc_u32 s7, s7, 0
	global_load_dwordx4 v[152:155], v9, s[6:7]
	s_add_u32 s6, s6, 0x1000
	s_addc_u32 s7, s7, 0
	global_load_dwordx4 v[156:159], v9, s[6:7]
	s_add_u32 s6, s6, 0x1000
	s_addc_u32 s7, s7, 0
	global_load_dwordx4 v[160:163], v9, s[6:7]
	s_waitcnt vmcnt(15)
	ds_write2st64_b32 v3, v100, v101 offset0:0 offset1:16
	ds_write2st64_b32 v3, v102, v103 offset0:32 offset1:48
	s_waitcnt vmcnt(14)
	ds_write2st64_b32 v3, v104, v105 offset0:1 offset1:17
	ds_write2st64_b32 v3, v106, v107 offset0:33 offset1:49
	s_waitcnt vmcnt(13)
	ds_write2st64_b32 v3, v108, v109 offset0:2 offset1:18
	ds_write2st64_b32 v3, v110, v111 offset0:34 offset1:50
	s_waitcnt vmcnt(12)
	ds_write2st64_b32 v3, v112, v113 offset0:3 offset1:19
	ds_write2st64_b32 v3, v114, v115 offset0:35 offset1:51
	s_waitcnt vmcnt(11)
	ds_write2st64_b32 v3, v116, v117 offset0:4 offset1:20
	ds_write2st64_b32 v3, v118, v119 offset0:36 offset1:52
	s_waitcnt vmcnt(10)
	ds_write2st64_b32 v3, v120, v121 offset0:5 offset1:21
	ds_write2st64_b32 v3, v122, v123 offset0:37 offset1:53
	s_waitcnt vmcnt(9)
	ds_write2st64_b32 v3, v124, v125 offset0:6 offset1:22
	ds_write2st64_b32 v3, v126, v127 offset0:38 offset1:54
	s_waitcnt vmcnt(8)
	ds_write2st64_b32 v3, v128, v129 offset0:7 offset1:23
	ds_write2st64_b32 v3, v130, v131 offset0:39 offset1:55
	s_waitcnt vmcnt(7)
	ds_write2st64_b32 v3, v132, v133 offset0:8 offset1:24
	ds_write2st64_b32 v3, v134, v135 offset0:40 offset1:56
	s_waitcnt vmcnt(6)
	ds_write2st64_b32 v3, v136, v137 offset0:9 offset1:25
	ds_write2st64_b32 v3, v138, v139 offset0:41 offset1:57
	s_waitcnt vmcnt(5)
	ds_write2st64_b32 v3, v140, v141 offset0:10 offset1:26
	ds_write2st64_b32 v3, v142, v143 offset0:42 offset1:58
	s_waitcnt vmcnt(4)
	ds_write2st64_b32 v3, v144, v145 offset0:11 offset1:27
	ds_write2st64_b32 v3, v146, v147 offset0:43 offset1:59
	s_waitcnt vmcnt(3)
	ds_write2st64_b32 v3, v148, v149 offset0:12 offset1:28
	ds_write2st64_b32 v3, v150, v151 offset0:44 offset1:60
	s_waitcnt vmcnt(2)
	ds_write2st64_b32 v3, v152, v153 offset0:13 offset1:29
	ds_write2st64_b32 v3, v154, v155 offset0:45 offset1:61
	s_waitcnt vmcnt(1)
	ds_write2st64_b32 v3, v156, v157 offset0:14 offset1:30
	ds_write2st64_b32 v3, v158, v159 offset0:46 offset1:62
	s_waitcnt vmcnt(0)
	ds_write2st64_b32 v3, v160, v161 offset0:15 offset1:31
	ds_write2st64_b32 v3, v162, v163 offset0:47 offset1:63
